# RNN loop: copy-out stores of the previous unit spread across the conv section (store issue overlapped with VALU) instead of issued back to back
# baseline (speedup 1.0000x reference)
; #define GAS __attribute__((address_space(1)))
; __device__ __forceinline__ void rnn_local_phase(Frame& F, const XcdBarrier& gbar, const bool use_bar) {
;     ...
;     const int cb = F.vcu % NRB, rank = F.vcu / NRB, cnt = (F.G - cb + NRB - 1) / NRB;
;     constexpr int NQ = BATCH * NCH;
;     const int nl = 16 * w + fr;
;     const int c = cb * 128 + nl;
;     bf16x8 br[2][4], bi[2][4];
; #pragma unroll
;     for (int dir = 0; dir < 2; ++dir) {
;         const bf16* wr_ = Wg_t + (size_t)((0 * 2 + dir) * NRB + cb) * 16384 + (size_t)nl * 128 + 8 * fq;
;         const bf16* wi_ = Wg_t + (size_t)((1 * 2 + dir) * NRB + cb) * 16384 + (size_t)nl * 128 + 8 * fq;
; #pragma unroll
;         for (int ks = 0; ks < 4; ++ks) { br[dir][ks] = *(const GAS bf16x8*)(wr_ + 32 * ks); bi[dir][ks] = *(const GAS bf16x8*)(wi_ + 32 * ks); }
;     }
;     bf16x8 idf;
;     { const bool on = (8 * fq) == ((16 * (w & 1) + fr) & ~7);
; #pragma unroll
;       for (int jj = 0; jj < 8; ++jj) idf[jj] = (short)((on && jj == (fr & 7)) ? 0x3F80 : 0); }
;     const int ksx = w >> 1;
;     float nba[2], nbx[2], kap[2];
; #pragma unroll
;     for (int dir = 0; dir < 2; ++dir) {
;         nba[dir] = -LOG2E * F.lru_ba[dir * DRNN + c]; nbx[dir] = -LOG2E * F.lru_bx[dir * DRNN + c];
;         const float lm = F.lam[dir * DRNN + c];
;         const float sp = fmaxf(-lm, 0.f) + log1pf(expf(-fabsf(lm)));
;         kap[dir] = -8.0f * sp * LOG2E;
;     }
;     const int cp = tid & 63;
;     float cw[4][2], cbias[2];
;     { const int cc = cb * 128 + 2 * cp;
; #pragma unroll
;       for (int jj = 0; jj < 4; ++jj) { cw[jj][0] = F.conv_w[jj * DRNN + cc]; cw[jj][1] = F.conv_w[jj * DRNN + cc + 1]; }
;       cbias[0] = F.conv_b[cc]; cbias[1] = F.conv_b[cc + 1]; }
;     const float mk0 = fq == 0 ? 1.f : 0.f, mk1 = fq == 1 ? 1.f : 0.f, mk2 = fq == 2 ? 1.f : 0.f, mk3 = fq == 3 ? 1.f : 0.f;
.LBB0_613:
	s_andn2_b64 vcc, exec, s[16:17]
	s_waitcnt vmcnt(0) lgkmcnt(0)
	s_barrier
	s_cbranch_vccnz .LBB0_625
	s_sub_i32 s0, s3, s0
	s_add_i32 s0, s0, 9
	s_add_u32 s9, s10, 0x2100000
	s_mul_hi_i32 s0, s0, 0x66666667
	v_and_b32_e32 v67, 24, v84
	s_addc_u32 s12, s11, 0
	s_lshr_b32 s1, s0, 31
	s_ashr_i32 s13, s0, 2
	v_cmp_eq_u32_e32 vcc, v64, v67
	v_and_b32_e32 v64, 7, v70
	s_add_i32 s13, s13, s1
	v_cmp_eq_u32_e64 s[0:1], 0, v64
	v_mov_b32_e32 v67, 0x3f80
	s_and_b64 s[0:1], s[0:1], vcc
	v_cndmask_b32_e64 v69, 0, v67, s[0:1]
	v_cmp_eq_u32_e64 s[0:1], 1, v64
	s_and_b64 s[0:1], s[0:1], vcc
	s_mov_b32 s2, 0xb2a5705f
	v_cndmask_b32_e64 v79, 0, v67, s[0:1]
	v_cmp_eq_u32_e64 s[0:1], 2, v64
	s_and_b64 s[0:1], s[0:1], vcc
	s_mov_b32 s4, 0x42ce8ed0
	v_cndmask_b32_e64 v80, 0, v67, s[0:1]
	v_cmp_eq_u32_e64 s[0:1], 3, v64
	s_and_b64 s[0:1], s[0:1], vcc
	s_mov_b32 s5, 0xc2b17218
	v_cndmask_b32_e64 v81, 0, v67, s[0:1]
	v_cmp_eq_u32_e64 s[0:1], 4, v64
	s_and_b64 s[0:1], s[0:1], vcc
	v_mov_b32_e32 v88, 0x7f800000
	v_cndmask_b32_e64 v82, 0, v67, s[0:1]
	v_cmp_eq_u32_e64 s[0:1], 5, v64
	s_and_b64 s[0:1], s[0:1], vcc
	s_mov_b32 s7, 0x3f2aaaab
	v_cndmask_b32_e64 v85, 0, v67, s[0:1]
	v_cmp_eq_u32_e64 s[0:1], 6, v64
	s_and_b64 s[0:1], s[0:1], vcc
	s_mov_b32 s14, 0x3f317218
	v_cndmask_b32_e64 v83, 0, v67, s[0:1]
	v_cmp_eq_u32_e64 s[0:1], 7, v64
	s_and_b64 vcc, s[0:1], vcc
	s_mov_b32 s1, 0xbfb8aa3b
	v_cndmask_b32_e32 v87, 0, v67, vcc
	v_mul_f32_e64 v67, |v76|, s1
	v_rndne_f32_e32 v68, v67
	v_sub_f32_e32 v75, v67, v68
	v_fma_f32 v67, |v76|, s1, -v67
	v_fma_f32 v67, |v76|, s2, v67
	v_add_f32_e32 v67, v75, v67
	v_exp_f32_e32 v67, v67
	v_cvt_i32_f32_e32 v75, v68
	v_cmp_ngt_f32_e64 vcc, |v76|, s4
	v_mul_f32_e32 v64, 0xbfb8aa3b, v77
	v_max_f32_e64 v77, -v76, -v76
	v_ldexp_f32 v67, v67, v75
	v_cndmask_b32_e32 v67, 0, v67, vcc
	v_cmp_nlt_f32_e64 vcc, |v76|, s5
	v_mul_f32_e32 v68, 0xbfb8aa3b, v78
	v_max_f32_e32 v78, 0, v77
	v_cndmask_b32_e32 v67, v88, v67, vcc
	v_add_f32_e32 v75, 1.0, v67
	v_add_f32_e32 v76, -1.0, v75
	v_sub_f32_e32 v77, v76, v75
	v_add_f32_e32 v77, 1.0, v77
	v_sub_f32_e32 v76, v67, v76
	v_add_f32_e32 v89, v76, v77
	v_frexp_mant_f32_e32 v90, v75
	v_cvt_f64_f32_e32 v[76:77], v75
	v_frexp_exp_i32_f64_e32 v76, v[76:77]
	v_cmp_gt_f32_e32 vcc, s7, v90
	s_mov_b32 s0, 0x7f800000
	s_mov_b32 s15, 0x33800000
	v_subbrev_co_u32_e32 v76, vcc, 0, v76, vcc
	v_sub_u32_e32 v77, 0, v76
	v_ldexp_f32 v75, v75, v77
	v_ldexp_f32 v77, v89, v77
	v_add_f32_e32 v89, -1.0, v75
	v_add_f32_e32 v92, 1.0, v75
	v_add_f32_e32 v90, 1.0, v89
	v_add_f32_e32 v93, -1.0, v92
	v_sub_f32_e32 v90, v75, v90
	v_sub_f32_e32 v75, v75, v93
	v_add_f32_e32 v75, v77, v75
	v_add_f32_e32 v90, v77, v90
	v_add_f32_e32 v77, v92, v75
	v_rcp_f32_e32 v93, v77
	v_add_f32_e32 v91, v89, v90
	v_sub_f32_e32 v89, v89, v91
	v_add_f32_e32 v89, v90, v89
	v_sub_f32_e32 v90, v92, v77
	v_add_f32_e32 v75, v75, v90
	v_mul_f32_e32 v90, v91, v93
	v_mul_f32_e32 v92, v77, v90
	v_fma_f32 v94, v90, v77, -v92
	v_fmac_f32_e32 v94, v90, v75
	v_add_f32_e32 v95, v92, v94
	v_sub_f32_e32 v96, v91, v95
	v_sub_f32_e32 v91, v91, v96
	v_sub_f32_e32 v92, v95, v92
	v_sub_f32_e32 v91, v91, v95
	v_add_f32_e32 v89, v89, v91
	v_sub_f32_e32 v91, v92, v94
	v_add_f32_e32 v89, v91, v89
	v_add_f32_e32 v91, v96, v89
	v_mul_f32_e32 v92, v93, v91
	v_mul_f32_e32 v94, v77, v92
	v_fma_f32 v77, v92, v77, -v94
	v_fmac_f32_e32 v77, v92, v75
	v_sub_f32_e32 v75, v96, v91
	v_add_f32_e32 v75, v89, v75
	v_add_f32_e32 v89, v94, v77
	v_sub_f32_e32 v95, v91, v89
	v_sub_f32_e32 v91, v91, v95
	v_sub_f32_e32 v94, v89, v94
	v_sub_f32_e32 v89, v91, v89
	v_add_f32_e32 v75, v75, v89
	v_sub_f32_e32 v77, v94, v77
	v_cvt_f32_i32_e32 v76, v76
	v_add_f32_e32 v75, v77, v75
	v_add_f32_e32 v77, v90, v92
	v_add_f32_e32 v75, v95, v75
	v_sub_f32_e32 v89, v77, v90
	v_mul_f32_e32 v75, v93, v75
	v_sub_f32_e32 v89, v92, v89
	v_add_f32_e32 v75, v89, v75
	v_mul_f32_e32 v94, 0x3f317218, v76
	v_add_f32_e32 v89, v77, v75
	v_fma_f32 v95, v76, s14, -v94
	v_mul_f32_e32 v90, v89, v89
	v_mov_b32_e32 v91, 0x3ecc95a3
	v_fmac_f32_e32 v95, 0xb102e308, v76
	v_sub_f32_e32 v76, v89, v77
	v_fmamk_f32 v92, v90, 0x3e9b6dac, v91
	v_sub_f32_e32 v75, v75, v76
	v_add_f32_e32 v76, v94, v95
	v_fmaak_f32 v92, v90, v92, 0x3f2aaada
	v_sub_f32_e32 v77, v76, v94
	v_ldexp_f32 v94, v89, 1
	v_mul_f32_e32 v89, v89, v90
	v_mul_f32_e32 v89, v89, v92
	v_add_f32_e32 v90, v94, v89
	v_sub_f32_e32 v92, v90, v94
	v_ldexp_f32 v75, v75, 1
	v_sub_f32_e32 v89, v89, v92
	v_add_f32_e32 v75, v75, v89
	v_add_f32_e32 v89, v90, v75
	v_sub_f32_e32 v90, v89, v90
	v_sub_f32_e32 v75, v75, v90
	v_add_f32_e32 v90, v76, v89
	v_sub_f32_e32 v92, v90, v76
	v_sub_f32_e32 v94, v90, v92
	v_sub_f32_e32 v77, v95, v77
	v_sub_f32_e32 v76, v76, v94
	v_sub_f32_e32 v89, v89, v92
	v_add_f32_e32 v76, v89, v76
	v_add_f32_e32 v89, v77, v75
	v_sub_f32_e32 v92, v89, v77
	v_sub_f32_e32 v94, v89, v92
	v_sub_f32_e32 v77, v77, v94
	v_sub_f32_e32 v75, v75, v92
	v_add_f32_e32 v76, v89, v76
	v_add_f32_e32 v75, v75, v77
	v_add_f32_e32 v77, v90, v76
	v_sub_f32_e32 v89, v77, v90
	v_sub_f32_e32 v76, v76, v89
	v_add_f32_e32 v75, v75, v76
	v_add_f32_e32 v75, v77, v75
	v_cmp_neq_f32_e32 vcc, s0, v67
	v_mov_b32_e32 v93, 0x3f2aaada
	v_readlane_b32 s21, v254, 4
	v_cndmask_b32_e32 v75, v88, v75, vcc
	v_cmp_lt_f32_e64 vcc, |v67|, s15
	v_mov_b32_e32 v172, 0
	v_mul_f32_e32 v72, 0xbfb8aa3b, v72
	v_cndmask_b32_e32 v67, v75, v67, vcc
	v_add_f32_e32 v67, v78, v67
	v_mul_f32_e32 v67, 0xc1000000, v67
	v_mul_f32_e32 v160, 0x3fb8aa3b, v67
	v_mul_f32_e64 v67, |v71|, s1
	v_rndne_f32_e32 v75, v67
	v_sub_f32_e32 v76, v67, v75
	v_fma_f32 v67, |v71|, s1, -v67
	v_fma_f32 v67, |v71|, s2, v67
; #define LAS __attribute__((address_space(3)))
; __device__ __forceinline__ void rnn_local_phase(Frame& F, const XcdBarrier& gbar, const bool use_bar) {
;     ...
;     float nba[2], nbx[2], kap[2];
; #pragma unroll
;     for (int dir = 0; dir < 2; ++dir) {
;         nba[dir] = -LOG2E * F.lru_ba[dir * DRNN + c]; nbx[dir] = -LOG2E * F.lru_bx[dir * DRNN + c];
;         const float lm = F.lam[dir * DRNN + c];
;         const float sp = fmaxf(-lm, 0.f) + log1pf(expf(-fabsf(lm)));
;         kap[dir] = -8.0f * sp * LOG2E;
;     }
;     const int cp = tid & 63;
;     float cw[4][2], cbias[2];
;     { const int cc = cb * 128 + 2 * cp;
; #pragma unroll
;       for (int jj = 0; jj < 4; ++jj) { cw[jj][0] = F.conv_w[jj * DRNN + cc]; cw[jj][1] = F.conv_w[jj * DRNN + cc + 1]; }
;       cbias[0] = F.conv_b[cc]; cbias[1] = F.conv_b[cc + 1]; }
;     const float mk0 = fq == 0 ? 1.f : 0.f, mk1 = fq == 1 ? 1.f : 0.f, mk2 = fq == 2 ? 1.f : 0.f, mk3 = fq == 3 ? 1.f : 0.f;
;     ...
;     int q = rank;
;     if (q < NQ) RNN_DMA(q);
;     if (use_bar) xcd_wait(gbar, tok);
;     __builtin_amdgcn_s_waitcnt(0x0F70);
;     __syncthreads();
;     for (; q < NQ; q += cnt) {
;         const int b = q / NCH, j = q % NCH, t0 = b * SEQ + j * LCH;
;         const bool has_next = (q + cnt) < NQ;
;         {
;             float x0[11], x1[11];
; #pragma unroll
;             for (int r = 0; r < 11; ++r) { const unsigned v = *(const LAS unsigned*)(lds + R_RAW_OFF + (8 * w + r) * 256 + cp * 4); x0[r] = bflo(v); x1[r] = bfhi(v); }
;             if (j == 0 && w == 0) { x0[0] = 0.f; x1[0] = 0.f; x0[1] = 0.f; x1[1] = 0.f; }
;             if (j == NCH - 1 && w == NWAVES - 1) { x0[10] = 0.f; x1[10] = 0.f; }
; #pragma unroll
;             for (int t8 = 0; t8 < 8; ++t8) {
;                 const int tt = 8 * w + t8;
;                 float y0 = cbias[0], y1 = cbias[1];
; #pragma unroll
;                 for (int jj = 0; jj < 4; ++jj) { y0 += cw[jj][0] * x0[t8 + jj]; y1 += cw[jj][1] * x1[t8 + jj]; }
;                 *(LAS unsigned*)(lds + R_A_OFF + tt * 256 + (((cp >> 2) ^ (tt & 15)) << 4) + (cp & 3) * 4) = cvt_pk_bf16(y0, y1);
;             }
;         }
;         __syncthreads();
;         if (has_next) RNN_DMA(q + cnt);
;         float Pc[2] = {1.f, 1.f}, Hc[2] = {0.f, 0.f};
;         f2 hkeep[2][4];
;         LAS bf16* const stH = (LAS bf16*)(lds + R_ST_OFF) + (4 * fq) * 128 + nl;
	v_add_f32_e32 v67, v76, v67
	v_exp_f32_e32 v67, v67
	v_cvt_i32_f32_e32 v75, v75
	v_cmp_ngt_f32_e64 vcc, |v71|, s4
	v_mul_f32_e32 v76, 0xbfb8aa3b, v74
	v_max_f32_e64 v74, -v71, -v71
	v_ldexp_f32 v67, v67, v75
	v_cndmask_b32_e32 v67, 0, v67, vcc
	v_cmp_nlt_f32_e64 vcc, |v71|, s5
	v_max_f32_e32 v77, 0, v74
	v_readlane_b32 s2, v254, 5
	v_cndmask_b32_e32 v67, v88, v67, vcc
	v_add_f32_e32 v71, 1.0, v67
	v_add_f32_e32 v74, -1.0, v71
	v_sub_f32_e32 v75, v74, v71
	v_add_f32_e32 v75, 1.0, v75
	v_sub_f32_e32 v74, v67, v74
	v_add_f32_e32 v78, v74, v75
	v_frexp_mant_f32_e32 v89, v71
	v_cvt_f64_f32_e32 v[74:75], v71
	v_frexp_exp_i32_f64_e32 v74, v[74:75]
	v_cmp_gt_f32_e32 vcc, s7, v89
	s_mov_b32 s17, 0
	v_mov_b32_e32 v161, v160
	v_subbrev_co_u32_e32 v74, vcc, 0, v74, vcc
	v_sub_u32_e32 v75, 0, v74
	v_ldexp_f32 v71, v71, v75
	v_ldexp_f32 v75, v78, v75
	v_add_f32_e32 v78, -1.0, v71
	v_add_f32_e32 v92, 1.0, v71
	v_add_f32_e32 v89, 1.0, v78
	v_add_f32_e32 v94, -1.0, v92
	v_sub_f32_e32 v89, v71, v89
	v_sub_f32_e32 v71, v71, v94
	v_add_f32_e32 v71, v75, v71
	v_add_f32_e32 v89, v75, v89
	v_add_f32_e32 v75, v92, v71
	v_rcp_f32_e32 v94, v75
	v_add_f32_e32 v90, v78, v89
	v_sub_f32_e32 v78, v78, v90
	v_add_f32_e32 v78, v89, v78
	v_sub_f32_e32 v89, v92, v75
	v_add_f32_e32 v71, v71, v89
	v_mul_f32_e32 v89, v90, v94
	v_mul_f32_e32 v92, v75, v89
	v_fma_f32 v95, v89, v75, -v92
	v_fmac_f32_e32 v95, v89, v71
	v_add_f32_e32 v96, v92, v95
	v_sub_f32_e32 v97, v90, v96
	v_sub_f32_e32 v90, v90, v97
	v_sub_f32_e32 v92, v96, v92
	v_sub_f32_e32 v90, v90, v96
	v_add_f32_e32 v78, v78, v90
	v_sub_f32_e32 v90, v92, v95
	v_add_f32_e32 v78, v90, v78
	v_add_f32_e32 v90, v97, v78
	v_mul_f32_e32 v92, v94, v90
	v_mul_f32_e32 v95, v75, v92
	v_fma_f32 v75, v92, v75, -v95
	v_fmac_f32_e32 v75, v92, v71
	v_sub_f32_e32 v71, v97, v90
	v_add_f32_e32 v71, v78, v71
	v_add_f32_e32 v78, v95, v75
	v_sub_f32_e32 v96, v90, v78
	v_sub_f32_e32 v90, v90, v96
	v_sub_f32_e32 v95, v78, v95
	v_sub_f32_e32 v78, v90, v78
	v_add_f32_e32 v71, v71, v78
	v_sub_f32_e32 v75, v95, v75
	v_add_f32_e32 v71, v75, v71
	v_add_f32_e32 v75, v89, v92
	v_add_f32_e32 v71, v96, v71
	v_sub_f32_e32 v78, v75, v89
	v_mul_f32_e32 v71, v94, v71
	v_sub_f32_e32 v78, v92, v78
	v_cvt_f32_i32_e32 v74, v74
	v_add_f32_e32 v71, v78, v71
	v_add_f32_e32 v78, v75, v71
	v_mul_f32_e32 v89, v78, v78
	v_fmac_f32_e32 v91, 0x3e9b6dac, v89
	v_mul_f32_e32 v90, 0x3f317218, v74
	v_fmac_f32_e32 v93, v89, v91
	v_fma_f32 v91, v74, s14, -v90
	v_fmac_f32_e32 v91, 0xb102e308, v74
	v_sub_f32_e32 v74, v78, v75
	v_sub_f32_e32 v71, v71, v74
	v_add_f32_e32 v74, v90, v91
	v_sub_f32_e32 v75, v74, v90
	v_ldexp_f32 v90, v78, 1
	v_mul_f32_e32 v78, v78, v89
	v_mul_f32_e32 v78, v78, v93
	v_add_f32_e32 v89, v90, v78
	v_sub_f32_e32 v90, v89, v90
	v_ldexp_f32 v71, v71, 1
	v_sub_f32_e32 v78, v78, v90
	v_add_f32_e32 v71, v71, v78
	v_add_f32_e32 v78, v89, v71
	v_sub_f32_e32 v89, v78, v89
	v_sub_f32_e32 v71, v71, v89
	v_add_f32_e32 v89, v74, v78
	v_sub_f32_e32 v90, v89, v74
	v_sub_f32_e32 v75, v91, v75
	v_sub_f32_e32 v91, v89, v90
	v_sub_f32_e32 v74, v74, v91
	v_sub_f32_e32 v78, v78, v90
	v_add_f32_e32 v74, v78, v74
	v_add_f32_e32 v78, v75, v71
	v_sub_f32_e32 v90, v78, v75
	v_sub_f32_e32 v91, v78, v90
	v_sub_f32_e32 v75, v75, v91
	v_sub_f32_e32 v71, v71, v90
	v_add_f32_e32 v74, v78, v74
	v_add_f32_e32 v71, v71, v75
	v_add_f32_e32 v75, v89, v74
	v_sub_f32_e32 v78, v75, v89
	v_sub_f32_e32 v74, v74, v78
	v_add_f32_e32 v71, v71, v74
	v_add_u32_e32 v90, s2, v70
	s_lshl_b32 s2, s21, 11
	v_add_f32_e32 v71, v75, v71
	v_cmp_neq_f32_e32 vcc, s0, v67
	s_add_i32 s2, s2, 0
	s_add_i32 s16, s2, 0x10000
	v_cndmask_b32_e32 v71, v88, v71, vcc
	v_cmp_lt_f32_e64 vcc, |v67|, s15
	s_cmp_eq_u32 s21, 7
	s_cselect_b64 s[4:5], -1, 0
	v_cndmask_b32_e32 v67, v71, v67, vcc
	v_add_f32_e32 v67, v77, v67
	s_ashr_i32 s7, s6, 31
	v_mul_f32_e32 v67, 0xc1000000, v67
	s_lshl_b32 s20, s21, 3
	s_lshl_b64 s[14:15], s[6:7], 1
	v_mul_f32_e32 v162, 0x3fb8aa3b, v67
	v_lshlrev_b32_e32 v67, 2, v70
	s_add_u32 s18, s33, s14
	v_and_b32_e32 v92, 12, v67
	s_addc_u32 s19, s34, s15
	v_mov_b32_e32 v67, v172
	v_lshl_add_u64 v[174:175], s[18:19], 0, v[66:67]
	s_lshl_b32 s18, s21, 1
	s_and_b32 s18, s18, 0x7fffffc
	s_add_u32 s14, s10, s14
	s_addc_u32 s15, s11, s15
	v_lshl_add_u64 v[66:67], s[14:15], 0, v[66:67]
	s_mov_b64 s[14:15], 0xe000000
	v_lshlrev_b32_e32 v91, 2, v65
	v_lshrrev_b32_e32 v65, 2, v65
	v_lshl_add_u64 v[176:177], v[66:67], 0, s[14:15]
	v_lshlrev_b32_e32 v66, 4, v70
	s_add_u32 s6, s10, s6
	v_and_b32_e32 v88, 0x70, v66
	s_addc_u32 s7, s11, s7
	v_mov_b32_e32 v89, v172
	v_bitop3_b32 v66, v65, s20, 8 bitop3:0x78
	v_lshl_add_u64 v[178:179], s[6:7], 0, v[88:89]
	v_lshl_add_u32 v89, v66, 4, s2
	s_or_b32 s2, s20, 1
	s_lshl_b32 s6, s2, 8
	s_add_i32 s6, s6, 0
	v_bitop3_b32 v66, v65, s2, 9 bitop3:0x78
	s_or_b32 s2, s20, 2
	v_lshl_add_u32 v97, v66, 4, s6
	s_lshl_b32 s6, s2, 8
	s_add_i32 s6, s6, 0
	v_bitop3_b32 v66, v65, s2, 10 bitop3:0x78
	s_or_b32 s2, s20, 3
	v_lshl_add_u32 v98, v66, 4, s6
	s_lshl_b32 s6, s2, 8
	s_add_i32 s6, s6, 0
	v_bitop3_b32 v66, v65, s2, 11 bitop3:0x78
	s_or_b32 s2, s20, 4
	v_lshl_add_u32 v99, v66, 4, s6
	s_lshl_b32 s6, s2, 8
	s_add_i32 s6, s6, 0
	v_bitop3_b32 v66, v65, s2, 12 bitop3:0x78
	s_or_b32 s2, s20, 5
	v_lshl_add_u32 v100, v66, 4, s6
	s_lshl_b32 s6, s2, 8
	s_add_i32 s6, s6, 0
	v_bitop3_b32 v66, v65, s2, 13 bitop3:0x78
	s_or_b32 s2, s20, 6
	v_lshl_add_u32 v101, v66, 4, s6
	s_lshl_b32 s6, s2, 8
	s_add_i32 s6, s6, 0
	v_bitop3_b32 v66, v65, s2, 14 bitop3:0x78
	s_or_b32 s2, s20, 7
	v_lshlrev_b32_e32 v71, 9, v86
	v_lshl_add_u32 v74, v86, 10, 0
	v_add_u32_e32 v75, s18, v86
	s_mov_b32 s18, 0x5040100
; #define GAS __attribute__((address_space(1)))
; #define LAS __attribute__((address_space(3)))
; __device__ __forceinline__ void rnn_local_phase(Frame& F, const XcdBarrier& gbar, const bool use_bar) {
;     ...
;     const float mk0 = fq == 0 ? 1.f : 0.f, mk1 = fq == 1 ? 1.f : 0.f, mk2 = fq == 2 ? 1.f : 0.f, mk3 = fq == 3 ? 1.f : 0.f;
;     ...
;     int q = rank;
;     if (q < NQ) RNN_DMA(q);
;     if (use_bar) xcd_wait(gbar, tok);
;     __builtin_amdgcn_s_waitcnt(0x0F70);
;     __syncthreads();
;     for (; q < NQ; q += cnt) {
;     ...
;         asm volatile("s_waitcnt lgkmcnt(0)" ::: "memory"); __builtin_amdgcn_s_barrier(); asm volatile("" ::: "memory");
; #pragma unroll
;         for (int k = 0; k < 2; ++k) { const int idx = tid + 512 * k, tok = idx >> 4, ch = idx & 15;
;             const v4u v = *(const LAS v4u*)(lds + R_ST_OFF + tok * 256 + ch * 16);
;             *(GAS v4u*)(HL + (size_t)(t0 + tok) * DRNN + cb * 128 + ch * 8) = v; }
; #pragma unroll
;         for (int arr = 1; arr < 3; ++arr) {
;             unsigned char* dst = arr == 1 ? (unsigned char*)PF : (unsigned char*)PB; const int tok = tid >> 3, ch = tid & 7;
;             const v4u v = *(const LAS v4u*)(lds + R_ST_OFF + arr * 16384 + tok * 128 + ch * 16);
;             *(GAS v4u*)(dst + (size_t)(t0 + tok) * DRNN + cb * 128 + ch * 16) = v; }
	v_lshl_add_u32 v102, v66, 4, s6
	s_lshl_b32 s6, s2, 8
	v_lshl_add_u32 v206, v84, 1, v74
	v_perm_b32 v82, v85, v82, s18
	v_sub_u32_e32 v85, v74, v71
	s_add_i32 s6, s6, 0
	v_xor_b32_e32 v74, v86, v73
	v_bitop3_b32 v65, v65, s2, 15 bitop3:0x78
	s_cmpk_lt_u32 s48, 0x440
	v_lshlrev_b32_e32 v104, 4, v74
	v_add_u32_e32 v74, 4, v86
	v_lshl_add_u32 v103, v65, 4, s6
	s_cselect_b64 s[6:7], -1, 0
	s_lshl_b32 s2, s21, 2
	s_lshl_b32 s22, s21, 10
	v_xor_b32_e32 v74, v74, v73
	v_ashrrev_i32_e32 v95, 3, v90
	s_cmpk_lt_u32 s48, 0x240
	v_lshlrev_b32_e32 v105, 4, v74
	v_add_u32_e32 v74, 8, v86
	v_ashrrev_i32_e32 v108, 4, v90
	v_add_u32_e32 v90, 0x200, v90
	v_cmp_eq_u32_e32 vcc, 1, v86
	s_cselect_b64 s[14:15], -1, 0
	v_xor_b32_e32 v74, v74, v73
	v_ashrrev_i32_e32 v90, 4, v90
	s_lshl_b32 s20, s8, 6
	v_cndmask_b32_e64 v166, 0, 1.0, vcc
	v_cmp_eq_u32_e32 vcc, 2, v86
	v_lshl_add_u32 v93, v73, 8, 0
	v_perm_b32 v83, v87, v83, s18
	v_perm_b32 v81, v81, v80, s18
	v_perm_b32 v80, v79, v69, s18
	s_movk_i32 s18, 0xff10
	v_lshlrev_b32_e32 v106, 4, v74
	v_add_u32_e32 v74, 12, v86
	v_add_u32_e32 v207, s20, v95
	v_add_u32_e32 v208, s20, v90
	v_add_u32_e32 v209, s20, v108
	s_add_i32 s20, s8, s13
	v_cmp_gt_u32_e64 s[0:1], 16, v70
	v_cndmask_b32_e64 v168, 0, 1.0, vcc
	v_cmp_eq_u32_e32 vcc, 3, v86
	v_xor_b32_e32 v75, v75, v73
	v_mad_i32_i24 v87, v73, s18, v93
	s_add_i32 s18, s22, 0x2000
	s_add_i32 s19, s22, 0x4000
	v_xor_b32_e32 v73, v74, v73
	s_lshl_b32 s20, s20, 6
	v_cndmask_b32_e64 v164, 0, 1.0, s[0:1]
	v_cndmask_b32_e64 v170, 0, 1.0, vcc
	v_lshlrev_b32_e32 v94, 4, v75
	v_lshl_add_u32 v96, v95, 7, 0
	v_lshlrev_b32_e32 v107, 4, v73
	v_lshlrev_b32_e32 v109, 8, v108
	v_lshlrev_b32_e32 v110, 8, v90
	s_add_i32 s2, s2, s20
	s_add_i32 s25, s18, 0
	s_add_i32 s26, s19, 0
	v_mov_b32_e32 v65, v64
	v_mov_b32_e32 v66, v64
	v_mov_b32_e32 v67, v64
	v_mov_b32_e32 v69, v68
	v_mov_b32_e32 v70, v68
	v_mov_b32_e32 v71, v68
	v_mov_b32_e32 v73, v72
	v_mov_b32_e32 v74, v72
	v_mov_b32_e32 v75, v72
	v_mov_b32_e32 v77, v76
	v_mov_b32_e32 v78, v76
	v_mov_b32_e32 v79, v76
	v_mov_b32_e32 v163, v162
	v_mov_b32_e32 v171, v170
	v_mov_b32_e32 v169, v168
	v_mov_b32_e32 v167, v166
	v_mov_b32_e32 v165, v164
	s_lshl_b32 s23, s13, 6
	v_add_u32_e32 v210, s2, v86
	v_add_u32_e32 v211, s16, v91
	v_add_u32_e32 v212, v89, v92
	v_add_u32_e32 v213, v97, v92
	v_add_u32_e32 v214, v98, v92
	v_add_u32_e32 v215, v99, v92
	v_add_u32_e32 v216, v100, v92
	v_add_u32_e32 v217, v101, v92
	v_add_u32_e32 v218, v102, v92
	v_add_u32_e32 v219, v103, v92
	s_movk_i32 s24, 0xa00
	s_add_i32 s25, s25, 0x10000
	s_add_i32 s26, s26, 0x10000
	v_add_u32_e32 v220, v93, v94
	v_add_u32_e32 v221, v93, v104
	v_add_u32_e32 v222, v93, v105
	v_add_u32_e32 v223, v93, v106
	v_add_u32_e32 v224, v93, v107
	s_mov_b32 s16, 0x437f0000
	v_add_u32_e32 v225, v85, v84
	v_add_u32_e32 v226, v87, v109
	v_add_u32_e32 v227, v87, v110
	s_movk_i32 s27, 0x500
	v_add_u32_e32 v228, v96, v88
	v_mov_b32_e32 v229, 0x3fff
	v_mov_b32_e32 v180, 1.0
	s_mov_b64 s[100:101], 0
	s_branch .LBB0_616
.LBB0_615:
	s_or_b64 exec, exec, s[20:21]
	s_waitcnt lgkmcnt(0)
	s_barrier
	ds_read_b128 v[112:115], v226 offset:16384
	ds_read_b128 v[116:119], v227 offset:16384
	ds_read_b128 v[120:123], v228 offset:32768
	ds_read_b128 v[124:127], v228 offset:49152
	v_add_u32_e32 v88, s17, v209
	v_mad_i64_i32 v[128:129], s[20:21], v88, s24, v[176:177]
	s_mov_b32 s8, s33
	v_add_u32_e32 v84, s17, v208
	v_mad_i64_i32 v[130:131], s[20:21], v84, s24, v[176:177]
	v_add_u32_e32 v84, s17, v207
	v_mad_i64_i32 v[92:93], s[20:21], v84, s27, v[178:179]
	s_add_i32 s17, s17, s23
	s_nop 1
	v_add_co_u32_e32 v132, vcc, 0x13000000, v92
	s_nop 1
	v_addc_co_u32_e32 v133, vcc, 0, v93, vcc
	v_add_co_u32_e32 v134, vcc, 0x18000000, v92
	s_nop 1
	v_addc_co_u32_e32 v135, vcc, 0, v93, vcc
	s_andn2_b64 vcc, exec, s[18:19]
	s_waitcnt lgkmcnt(0)
	global_store_dwordx4 v[128:129], v[112:115], off
	s_cbranch_vccz .Lrnn_flush
	s_mov_b64 s[100:101], -1
; __device__ __forceinline__ unsigned cvt_pk_bf16(float lo, float hi) { unsigned r; asm volatile("v_cvt_pk_bf16_f32 %0, %1, %2" : "=v"(r) : "v"(lo), "v"(hi)); return r; }
; #define LAS __attribute__((address_space(3)))
; __device__ __forceinline__ float bflo(unsigned w) { return __uint_as_float(w << 16); }
; __device__ __forceinline__ float bfhi(unsigned w) { return __uint_as_float(w & 0xffff0000u); }
; __device__ __forceinline__ void rnn_local_phase(Frame& F, const XcdBarrier& gbar, const bool use_bar) {
;     ...
;     for (; q < NQ; q += cnt) {
;         const int b = q / NCH, j = q % NCH, t0 = b * SEQ + j * LCH;
;         const bool has_next = (q + cnt) < NQ;
;         {
;             float x0[11], x1[11];
; #pragma unroll
;             for (int r = 0; r < 11; ++r) { const unsigned v = *(const LAS unsigned*)(lds + R_RAW_OFF + (8 * w + r) * 256 + cp * 4); x0[r] = bflo(v); x1[r] = bfhi(v); }
;             if (j == 0 && w == 0) { x0[0] = 0.f; x1[0] = 0.f; x0[1] = 0.f; x1[1] = 0.f; }
;             if (j == NCH - 1 && w == NWAVES - 1) { x0[10] = 0.f; x1[10] = 0.f; }
; #pragma unroll
;             for (int t8 = 0; t8 < 8; ++t8) {
;                 const int tt = 8 * w + t8;
;                 float y0 = cbias[0], y1 = cbias[1];
; #pragma unroll
;                 for (int jj = 0; jj < 4; ++jj) { y0 += cw[jj][0] * x0[t8 + jj]; y1 += cw[jj][1] * x1[t8 + jj]; }
;                 *(LAS unsigned*)(lds + R_A_OFF + tt * 256 + (((cp >> 2) ^ (tt & 15)) << 4) + (cp & 3) * 4) = cvt_pk_bf16(y0, y1);
;             }
;         }
;         __syncthreads();
;         if (has_next) RNN_DMA(q + cnt);
.LBB0_616:
	s_ashr_i32 s2, s8, 31
	s_lshr_b32 s2, s2, 24
	s_add_i32 s2, s8, s2
	s_and_b32 s2, s2, 0xffffff00
	ds_read2st64_b32 v[84:85], v211 offset1:1
	s_sub_i32 s2, s8, s2
	s_add_i32 s33, s8, s13
	s_cmpk_gt_i32 s33, 0x1ff
	v_readlane_b32 s20, v254, 4
	s_cselect_b64 s[18:19], -1, 0
	s_or_b32 s20, s2, s20
	s_cmp_eq_u32 s20, 0
	ds_read2st64_b32 v[86:87], v211 offset0:2 offset1:3
	ds_read2st64_b32 v[88:89], v211 offset0:4 offset1:5
	ds_read2st64_b32 v[90:91], v211 offset0:6 offset1:7
	s_waitcnt lgkmcnt(0)
	v_lshlrev_b32_e32 v92, 16, v84
	s_cselect_b64 s[20:21], -1, 0
	v_lshlrev_b32_e32 v93, 16, v85
	v_and_b32_e32 v95, 0xffff0000, v84
	v_cndmask_b32_e64 v92, v92, 0, s[20:21]
	v_and_b32_e32 v94, 0xffff0000, v85
	v_cndmask_b32_e64 v93, v93, 0, s[20:21]
	v_cndmask_b32_e64 v95, v95, 0, s[20:21]
	v_fma_f32 v92, v150, v92, v158
	s_waitcnt lgkmcnt(2)
	v_lshlrev_b32_e32 v96, 16, v86
	v_cndmask_b32_e64 v94, v94, 0, s[20:21]
	v_fma_f32 v95, v151, v95, v159
	v_fmac_f32_e32 v92, v152, v93
	v_and_b32_e32 v86, 0xffff0000, v86
	v_lshlrev_b32_e32 v97, 16, v87
	v_fmac_f32_e32 v95, v153, v94
	v_fmac_f32_e32 v92, v154, v96
	v_and_b32_e32 v87, 0xffff0000, v87
	v_fmac_f32_e32 v95, v155, v86
	v_fmac_f32_e32 v92, v156, v97
	ds_read2st64_b32 v[84:85], v211 offset0:8 offset1:9
	ds_read_b32 v102, v211 offset:2560
	v_fmac_f32_e32 v95, v157, v87
	v_cvt_pk_bf16_f32 v92, v92, v95
	ds_write_b32 v212, v92
	v_fma_f32 v92, v150, v93, v158
	v_fma_f32 v93, v151, v94, v159
	v_fmac_f32_e32 v92, v152, v96
	s_waitcnt lgkmcnt(4)
	v_lshlrev_b32_e32 v98, 16, v88
	v_fmac_f32_e32 v93, v153, v86
	v_fmac_f32_e32 v92, v154, v97
	v_and_b32_e32 v88, 0xffff0000, v88
	v_fmac_f32_e32 v93, v155, v87
	v_fmac_f32_e32 v92, v156, v98
	v_fmac_f32_e32 v93, v157, v88
	v_cvt_pk_bf16_f32 v92, v92, v93
	v_fma_f32 v86, v151, v86, v159
	ds_write_b32 v213, v92
	s_mov_b64 exec, s[100:101]
	global_store_dwordx4 v[130:131], v[116:119], off
	s_mov_b64 exec, -1
	v_fma_f32 v92, v150, v96, v158
	v_fmac_f32_e32 v86, v153, v87
	v_lshlrev_b32_e32 v99, 16, v89
	v_and_b32_e32 v89, 0xffff0000, v89
	v_fmac_f32_e32 v92, v152, v97
	v_fmac_f32_e32 v86, v155, v88
	v_fmac_f32_e32 v92, v154, v98
	v_fmac_f32_e32 v86, v157, v89
	v_fmac_f32_e32 v92, v156, v99
	v_cvt_pk_bf16_f32 v86, v92, v86
	ds_write_b32 v214, v86
	v_fma_f32 v86, v150, v97, v158
	v_fma_f32 v87, v151, v87, v159
	v_fmac_f32_e32 v86, v152, v98
	s_waitcnt lgkmcnt(5)
	v_lshlrev_b32_e32 v100, 16, v90
	v_fmac_f32_e32 v87, v153, v88
	v_fmac_f32_e32 v86, v154, v99
	v_and_b32_e32 v90, 0xffff0000, v90
	v_fmac_f32_e32 v87, v155, v89
	v_fmac_f32_e32 v86, v156, v100
	v_fmac_f32_e32 v87, v157, v90
	v_cvt_pk_bf16_f32 v86, v86, v87
	ds_write_b32 v215, v86
	s_mov_b64 exec, s[100:101]
	global_store_dwordx4 v[132:133], v[120:123], off
	s_mov_b64 exec, -1
	v_fma_f32 v86, v150, v98, v158
	v_fma_f32 v87, v151, v88, v159
	v_fmac_f32_e32 v86, v152, v99
	v_lshlrev_b32_e32 v101, 16, v91
	v_fmac_f32_e32 v87, v153, v89
	v_fmac_f32_e32 v86, v154, v100
	v_and_b32_e32 v91, 0xffff0000, v91
	v_fmac_f32_e32 v87, v155, v90
	v_fmac_f32_e32 v86, v156, v101
	v_fmac_f32_e32 v87, v157, v91
	v_cvt_pk_bf16_f32 v86, v86, v87
	ds_write_b32 v216, v86
	v_fma_f32 v86, v150, v99, v158
	v_fma_f32 v87, v151, v89, v159
	v_fmac_f32_e32 v86, v152, v100
	s_waitcnt lgkmcnt(0)
	v_lshlrev_b32_e32 v103, 16, v84
	v_fmac_f32_e32 v87, v153, v90
	v_fmac_f32_e32 v86, v154, v101
	v_and_b32_e32 v84, 0xffff0000, v84
	v_fmac_f32_e32 v87, v155, v91
	v_fmac_f32_e32 v86, v156, v103
	v_fmac_f32_e32 v87, v157, v84
	v_cvt_pk_bf16_f32 v86, v86, v87
	ds_write_b32 v217, v86
	s_mov_b64 exec, s[100:101]
	global_store_dwordx4 v[134:135], v[124:127], off
	s_mov_b64 exec, -1
	v_fma_f32 v86, v150, v100, v158
	v_fma_f32 v87, v151, v90, v159
	v_fmac_f32_e32 v86, v152, v101
	v_lshlrev_b32_e32 v104, 16, v85
	v_fmac_f32_e32 v87, v153, v91
	v_fmac_f32_e32 v86, v154, v103
	v_and_b32_e32 v85, 0xffff0000, v85
	v_fmac_f32_e32 v87, v155, v84
	v_fmac_f32_e32 v86, v156, v104
	s_cmpk_eq_i32 s2, 0xff
	v_fmac_f32_e32 v87, v157, v85
	v_cvt_pk_bf16_f32 v86, v86, v87
	s_cselect_b64 s[20:21], -1, 0
	ds_write_b32 v218, v86
	v_fma_f32 v86, v150, v101, v158
	v_fma_f32 v87, v151, v91, v159
	s_waitcnt lgkmcnt(7)
	v_lshlrev_b32_e32 v105, 16, v102
	v_and_b32_e32 v102, 0xffff0000, v102
	s_and_b64 s[20:21], s[4:5], s[20:21]
	v_fmac_f32_e32 v86, v152, v103
	v_fmac_f32_e32 v87, v153, v84
	v_cndmask_b32_e64 v102, v102, 0, s[20:21]
	v_cndmask_b32_e64 v105, v105, 0, s[20:21]
	v_fmac_f32_e32 v86, v154, v104
	v_fmac_f32_e32 v87, v155, v85
	s_and_b64 vcc, exec, s[18:19]
	v_fmac_f32_e32 v86, v156, v105
	v_fmac_f32_e32 v87, v157, v102
	v_cvt_pk_bf16_f32 v84, v86, v87
	ds_write_b32 v219, v84
	s_waitcnt lgkmcnt(0)
	s_barrier
	s_cbranch_vccnz .LBB0_623
	s_ashr_i32 s2, s33, 31
	s_lshr_b32 s2, s2, 24
	s_add_i32 s2, s33, s2
	s_ashr_i32 s2, s2, 8
	s_lshl_b32 s20, s2, 14
	v_add_u32_e32 v84, s17, v210
	s_andn2_b64 vcc, exec, s[6:7]
	v_subrev_u32_e32 v84, s20, v84
	s_cbranch_vccnz .LBB0_619
	v_add_u32_e32 v85, -2, v84
	v_med3_i32 v85, v85, 0, v229
	v_or_b32_e32 v85, s20, v85
	s_add_i32 s2, s22, 0
	v_mad_i64_i32 v[86:87], s[34:35], v85, s24, v[174:175]
	s_add_i32 m0, s2, 0x10000
	s_nop 0
	global_load_lds_dwordx4 v[86:87], off nt

; #define GAS __attribute__((address_space(1)))
; #define LAS __attribute__((address_space(3)))
; __device__ __forceinline__ void rnn_local_phase(Frame& F, const XcdBarrier& gbar, const bool use_bar) {
;     ...
;         for (int k = 0; k < 2; ++k) { const int idx = tid + 512 * k, tok = idx >> 4, ch = idx & 15;
;             const v4u v = *(const LAS v4u*)(lds + R_ST_OFF + tok * 256 + ch * 16);
;             *(GAS v4u*)(HL + (size_t)(t0 + tok) * DRNN + cb * 128 + ch * 8) = v; }
; #pragma unroll
;         for (int arr = 1; arr < 3; ++arr) {
;             unsigned char* dst = arr == 1 ? (unsigned char*)PF : (unsigned char*)PB; const int tok = tid >> 3, ch = tid & 7;
;             const v4u v = *(const LAS v4u*)(lds + R_ST_OFF + arr * 16384 + tok * 128 + ch * 16);
;             *(GAS v4u*)(dst + (size_t)(t0 + tok) * DRNN + cb * 128 + ch * 16) = v; }
.Lrnn_flush:
	global_store_dwordx4 v[130:131], v[116:119], off
	global_store_dwordx4 v[132:133], v[120:123], off
	global_store_dwordx4 v[134:135], v[124:127], off
